# v020 + attention QK block: all eight K-fragment LDS addresses formed before the first MFMA (no VALU between MFMAs)
# speedup vs baseline: 1.0048x; 1.0039x over previous
.LBB0_2765:
	s_andn2_b64 vcc, exec, s[8:9]
	s_cbranch_vccnz .LBB0_2775
	s_and_b32 s22, s21, 0x8000
	v_ashrrev_i32_e32 v16, 5, v242
	v_and_b32_e32 v2, 31, v242
	s_add_i32 s8, s43, s22
	v_lshlrev_b32_e32 v17, 4, v16
	v_lshlrev_b32_e32 v190, 4, v242
	v_and_b32_e32 v190, 0x70, v190
	v_lshl_add_u32 v191, v2, 8, s8
	v_xad_u32 v192, v17, v190, v191
	v_add_u32_e32 v193, 32, v17
	v_xad_u32 v193, v193, v190, v191
	ds_read_b128 v[4:7], v192
	ds_read_b128 v[8:11], v192 offset:8192
	ds_read_b128 v[12:15], v193
	ds_read_b128 v[178:181], v193 offset:8192
	v_add_u32_e32 v194, 64, v17
	v_xad_u32 v194, v194, v190, v191
	ds_read_b128 v[182:185], v194
	ds_read_b128 v[186:189], v194 offset:8192
	v_add_u32_e32 v195, 0x60, v17
	v_xad_u32 v195, v195, v190, v191
	v_add_u32_e32 v196, 0x80, v17
	v_xad_u32 v196, v196, v190, v191
	v_add_u32_e32 v197, 0xa0, v17
	v_xad_u32 v197, v197, v190, v191
	v_add_u32_e32 v198, 0xc0, v17
	v_xad_u32 v198, v198, v190, v191
	v_add_u32_e32 v199, 0xe0, v17
	v_xad_u32 v199, v199, v190, v191
	s_waitcnt lgkmcnt(0)
	v_mfma_f32_32x32x16_bf16 v[162:177], v[4:7], v[210:213], 0
	v_mfma_f32_32x32x16_bf16 v[146:161], v[8:11], v[210:213], 0
	ds_read_b128 v[4:7], v195
	ds_read_b128 v[8:11], v195 offset:8192
	v_mfma_f32_32x32x16_bf16 v[162:177], v[12:15], v[214:217], v[162:177]
	v_mfma_f32_32x32x16_bf16 v[146:161], v[178:181], v[214:217], v[146:161]
	ds_read_b128 v[12:15], v196
	ds_read_b128 v[178:181], v196 offset:8192
	v_mfma_f32_32x32x16_bf16 v[162:177], v[182:185], v[218:221], v[162:177]
	v_mfma_f32_32x32x16_bf16 v[146:161], v[186:189], v[218:221], v[146:161]
	ds_read_b128 v[182:185], v197
	ds_read_b128 v[186:189], v197 offset:8192
	s_waitcnt lgkmcnt(0)
	v_mfma_f32_32x32x16_bf16 v[162:177], v[4:7], v[222:225], v[162:177]
	v_mfma_f32_32x32x16_bf16 v[146:161], v[8:11], v[222:225], v[146:161]
	ds_read_b128 v[4:7], v198
	ds_read_b128 v[8:11], v198 offset:8192
	v_mfma_f32_32x32x16_bf16 v[162:177], v[12:15], v[226:229], v[162:177]
	v_mfma_f32_32x32x16_bf16 v[146:161], v[178:181], v[226:229], v[146:161]
	ds_read_b128 v[12:15], v199
	ds_read_b128 v[178:181], v199 offset:8192
	v_mfma_f32_32x32x16_bf16 v[162:177], v[182:185], v[230:233], v[162:177]
	v_mfma_f32_32x32x16_bf16 v[146:161], v[186:189], v[230:233], v[146:161]
	s_waitcnt lgkmcnt(0)
	v_mfma_f32_32x32x16_bf16 v[162:177], v[4:7], v[234:237], v[162:177]
	v_mfma_f32_32x32x16_bf16 v[146:161], v[8:11], v[234:237], v[146:161]
	v_mfma_f32_32x32x16_bf16 v[162:177], v[12:15], v[238:241], v[162:177]
	v_mfma_f32_32x32x16_bf16 v[146:161], v[178:181], v[238:241], v[146:161]
	s_add_i32 s23, s18, s20
	s_add_i32 s10, s20, 63
	s_add_i32 s8, s23, 0xffffe0bf
	s_cmpk_lt_i32 s8, 0xffa6
	s_cselect_b64 s[8:9], -1, 0
	s_cmp_lt_i32 s10, s15
	s_cselect_b64 s[12:13], -1, 0
	s_and_b64 s[10:11], s[12:13], s[8:9]
	s_mov_b64 s[8:9], -1
	s_and_b64 vcc, exec, s[10:11]
	v_lshlrev_b32_e32 v11, 2, v16
	s_cbranch_vccnz .LBB0_2768
	v_sub_u32_e32 v2, v11, v2
	v_add_u32_e32 v2, s23, v2
	s_add_i32 s23, 0, 0x18600
	v_lshl_add_u32 v2, v2, 2, s23
	ds_read2_b32 v[178:179], v2 offset0:0 offset1:1
	ds_read2_b32 v[180:181], v2 offset0:2 offset1:3
	ds_read2_b32 v[182:183], v2 offset0:8 offset1:9
	ds_read2_b32 v[184:185], v2 offset0:10 offset1:11
	ds_read2_b32 v[186:187], v2 offset0:16 offset1:17
	ds_read2_b32 v[188:189], v2 offset0:18 offset1:19
	ds_read2_b32 v[190:191], v2 offset0:24 offset1:25
	ds_read2_b32 v[192:193], v2 offset0:26 offset1:27
	ds_read2_b32 v[194:195], v2 offset0:32 offset1:33
	ds_read2_b32 v[196:197], v2 offset0:34 offset1:35
	ds_read2_b32 v[198:199], v2 offset0:40 offset1:41
	ds_read2_b32 v[200:201], v2 offset0:42 offset1:43
	ds_read2_b32 v[202:203], v2 offset0:48 offset1:49
	ds_read2_b32 v[204:205], v2 offset0:50 offset1:51
	ds_read2_b32 v[206:207], v2 offset0:56 offset1:57
	ds_read2_b32 v[208:209], v2 offset0:58 offset1:59
	s_waitcnt lgkmcnt(0)
	v_fmamk_f32 v162, v162, 0x3e0293ee, v178
	v_fmamk_f32 v146, v146, 0x3e0293ee, v194
	v_fmamk_f32 v163, v163, 0x3e0293ee, v179
	v_fmamk_f32 v147, v147, 0x3e0293ee, v195
	v_max_f32_e32 v2, v162, v146
	v_fmamk_f32 v164, v164, 0x3e0293ee, v180
	v_fmamk_f32 v148, v148, 0x3e0293ee, v196
	v_max3_f32 v2, v2, v163, v147
	v_fmamk_f32 v165, v165, 0x3e0293ee, v181
	v_fmamk_f32 v149, v149, 0x3e0293ee, v197
	v_max3_f32 v2, v2, v164, v148
	v_fmamk_f32 v166, v166, 0x3e0293ee, v182
	v_fmamk_f32 v150, v150, 0x3e0293ee, v198
	v_max3_f32 v2, v2, v165, v149
	v_fmamk_f32 v167, v167, 0x3e0293ee, v183
	v_fmamk_f32 v151, v151, 0x3e0293ee, v199
	v_max3_f32 v2, v2, v166, v150
	v_fmamk_f32 v168, v168, 0x3e0293ee, v184
	v_fmamk_f32 v152, v152, 0x3e0293ee, v200
	v_max3_f32 v2, v2, v167, v151
	v_fmamk_f32 v169, v169, 0x3e0293ee, v185
	v_fmamk_f32 v153, v153, 0x3e0293ee, v201
	v_max3_f32 v2, v2, v168, v152
	v_fmamk_f32 v170, v170, 0x3e0293ee, v186
	v_fmamk_f32 v154, v154, 0x3e0293ee, v202
	v_max3_f32 v2, v2, v169, v153
	v_fmamk_f32 v171, v171, 0x3e0293ee, v187
	v_fmamk_f32 v155, v155, 0x3e0293ee, v203
	v_max3_f32 v2, v2, v170, v154
	v_fmamk_f32 v172, v172, 0x3e0293ee, v188
	v_fmamk_f32 v156, v156, 0x3e0293ee, v204
	v_max3_f32 v2, v2, v171, v155
	v_fmamk_f32 v173, v173, 0x3e0293ee, v189
	v_fmamk_f32 v157, v157, 0x3e0293ee, v205
	v_max3_f32 v2, v2, v172, v156
	v_fmamk_f32 v174, v174, 0x3e0293ee, v190
	v_fmamk_f32 v158, v158, 0x3e0293ee, v206
	v_max3_f32 v2, v2, v173, v157
	v_fmamk_f32 v175, v175, 0x3e0293ee, v191
	v_fmamk_f32 v159, v159, 0x3e0293ee, v207
	v_max3_f32 v2, v2, v174, v158
	v_fmamk_f32 v176, v176, 0x3e0293ee, v192
	v_fmamk_f32 v160, v160, 0x3e0293ee, v208
	v_max3_f32 v2, v2, v175, v159
	v_fmamk_f32 v177, v177, 0x3e0293ee, v193
	v_fmamk_f32 v161, v161, 0x3e0293ee, v209
	v_max3_f32 v2, v2, v176, v160
	v_max3_f32 v4, v2, v177, v161
	s_mov_b64 s[8:9], 0
